# sample hgrn combine (k=4) runs behind the mixer phase on the idle workgroups: done-counter instead of a grid barrier between k=3 and k=4
# speedup vs baseline: 1.0046x; 1.0046x over previous
.LBB0_111:
.LBB0_112:
	s_add_i32 s36, s6, 1
	s_cmp_eq_u32 s6, 14
	s_cbranch_scc1 .LBB0_11
	s_cmp_eq_u32 s6, 34
	s_cbranch_scc1 .LBB0_11
	s_cmp_ge_i32 s36, s7
	s_cbranch_scc1 .LBB0_11
	v_readlane_b32 s4, v253, 46
	v_readlane_b32 s5, v253, 47
	s_andn2_b64 vcc, exec, s[4:5]
	s_cbranch_vccnz .LBB0_125
	s_waitcnt lgkmcnt(0)
	s_barrier
	s_mov_b64 s[4:5], exec
	v_readlane_b32 s20, v253, 48
	v_readlane_b32 s21, v253, 49
	s_and_b64 s[20:21], s[4:5], s[20:21]
	s_mov_b64 exec, s[20:21]
	s_cbranch_execz .LBB0_124
	v_readlane_b32 s12, v252, 0
	v_readlane_b32 s13, v252, 1
	buffer_wbl2 sc1
	s_waitcnt vmcnt(0)
	s_load_dwordx2 s[20:21], s[12:13], 0x58
	s_mov_b64 s[22:23], exec
	v_mbcnt_lo_u32_b32 v2, s22, 0
	v_mbcnt_hi_u32_b32 v2, s23, v2
	v_cmp_eq_u32_e32 vcc, 0, v2
	s_waitcnt lgkmcnt(0)
	global_load_dword v0, v1, s[20:21] offset:40
	s_and_saveexec_b64 s[24:25], vcc
	s_cbranch_execz .LBB0_117
	s_bcnt1_i32_b64 s6, s[22:23]
	v_mov_b32_e32 v3, s6
	global_atomic_add v3, v1, v3, s[20:21] offset:32 sc0

.LBB0_217:
	s_andn2_b64 vcc, exec, s[4:5]
	s_cbranch_vccnz .LBB0_534
	v_readlane_b32 s4, v255, 1
	s_cmp_lt_i32 s4, 2
	s_mov_b64 s[4:5], -1
	s_cbranch_scc1 .LBB0_507
	v_readlane_b32 s4, v255, 1
	s_cmp_lt_i32 s4, 3
	s_mov_b64 s[4:5], -1
	s_cbranch_scc1 .LBB0_309
	v_readlane_b32 s4, v255, 1
	s_cmp_gt_i32 s4, 3
	s_mov_b64 s[4:5], -1
	s_cbranch_scc0 .LBB0_225
	v_readlane_b32 s28, v252, 22
	v_readlane_b32 s44, v252, 4
	s_cmpk_lt_i32 s71, 0x100
	v_readlane_b32 s29, v252, 23
	v_readlane_b32 s30, v254, 39
	s_movk_i32 s31, 0x1400
	s_mov_b64 s[34:35], 0x6c26000
	s_mov_b32 s2, 0x6c26000
	v_readlane_b32 s45, v252, 5
	v_readlane_b32 s46, v252, 6
	v_readlane_b32 s47, v252, 7
	v_readlane_b32 s48, v252, 8
	v_readlane_b32 s49, v252, 9
	v_readlane_b32 s50, v252, 10
	v_readlane_b32 s51, v252, 11
	v_readlane_b32 s52, v252, 12
	v_readlane_b32 s53, v252, 13
	v_readlane_b32 s54, v252, 14
	v_readlane_b32 s55, v252, 15
	v_readlane_b32 s56, v252, 16
	v_readlane_b32 s57, v252, 17
	v_readlane_b32 s58, v252, 18
	v_readlane_b32 s59, v252, 19
	s_cbranch_scc1 .LBB0_224
	s_and_b64 s[4:5], s[12:13], exec
	s_mov_b32 s4, 0x4c25000
	s_cselect_b32 s4, s4, 0x9c25000
	s_add_u32 s4, s58, s4
	s_addc_u32 s5, s59, 0
	s_and_b64 s[20:21], s[12:13], exec
	s_mov_b32 s20, 0xfd25000
	s_cselect_b32 s20, s20, 0x6425000
	s_add_u32 s22, s58, s20
	v_readlane_b32 s14, v255, 2
	s_addc_u32 s23, s59, 0
	s_lshl_b32 s20, s14, 7
	s_mov_b64 s[36:37], s[44:45]
	s_ashr_i32 s21, s20, 31
	s_mov_b64 s[38:39], s[46:47]
	s_mov_b64 s[40:41], s[48:49]
	s_mov_b64 s[42:43], s[50:51]
	s_mov_b64 s[44:45], s[52:53]
	s_mov_b64 s[46:47], s[54:55]
	s_mov_b64 s[48:49], s[56:57]
	s_mov_b64 s[50:51], s[58:59]
	v_readlane_b32 s52, v253, 8
	s_lshl_b64 s[20:21], s[20:21], 2
	v_readlane_b32 s66, v253, 22
	v_readlane_b32 s53, v253, 9
	v_readlane_b32 s54, v253, 10
	v_readlane_b32 s55, v253, 11
	v_readlane_b32 s56, v253, 12
	v_readlane_b32 s57, v253, 13
	v_readlane_b32 s58, v253, 14
	v_readlane_b32 s59, v253, 15
	v_readlane_b32 s67, v253, 23
	s_add_u32 s26, s66, s20
	s_mov_b64 s[58:59], s[50:51]
	s_mov_b32 s75, 0x60000
	s_mov_b32 s76, 0x8000
	s_addc_u32 s27, s67, s21
	s_sub_i32 s21, s71, 0x100
	s_lshl_b32 s20, s21, 5
	v_readlane_b32 s15, v255, 3
	v_readlane_b32 s60, v253, 16
	v_readlane_b32 s61, v253, 17
	v_readlane_b32 s62, v253, 18
	v_readlane_b32 s63, v253, 19
	v_readlane_b32 s64, v253, 20
	v_readlane_b32 s65, v253, 21
	s_mov_b64 s[56:57], s[48:49]
	s_mov_b64 s[54:55], s[46:47]
	s_mov_b64 s[52:53], s[44:45]
	s_mov_b64 s[50:51], s[42:43]
	s_mov_b64 s[48:49], s[40:41]
	s_mov_b64 s[46:47], s[38:39]
	s_mov_b64 s[44:45], s[36:37]
	v_readlane_b32 s98, v255, 13
	v_readlane_b32 s99, v255, 14
	s_mov_b32 vcc_lo, 0
	s_nop 4
.Lfin_poll:
	global_load_dword v2, v1, s[98:99] sc1
	s_waitcnt vmcnt(0)
	v_readfirstlane_b32 vcc_hi, v2
	s_nop 3
	s_cmpk_ge_u32 vcc_hi, 0x100
	s_cbranch_scc1 .Lfin_go
	s_add_u32 vcc_lo, vcc_lo, 1
	s_cmpk_lt_u32 vcc_lo, 0x4000
	s_cbranch_scc0 .Lfin_go
	s_sleep 4
	s_branch .Lfin_poll

.LBB0_223:
	v_mov_b32_e32 v0, v1
	s_addk_i32 s21, 0x100
	v_mbcnt_lo_u32_b32 v0, -1, v0
	v_mbcnt_hi_u32_b32 v0, -1, v0
	v_add_u32_e32 v0, s80, v0
	s_nop 0
	v_ashrrev_i32_e32 v6, 3, v0
	s_waitcnt lgkmcnt(0)
	v_add_u32_e32 v2, s20, v6
	v_ashrrev_i32_e32 v2, 2, v2
	v_ashrrev_i32_e32 v3, 31, v2
	v_lshlrev_b64 v[4:5], 9, v[2:3]
	v_lshlrev_b32_e32 v3, 7, v6
	v_and_b32_e32 v8, 0x180, v3
	v_lshlrev_b32_e32 v0, 4, v0
	v_mov_b64_e32 v[6:7], s[58:59]
	v_and_b32_e32 v22, 0x70, v0
	v_mad_i64_i32 v[2:3], s[24:25], v2, s31, v[6:7]
	v_lshlrev_b32_e32 v0, 1, v8
	v_lshl_add_u64 v[2:3], v[2:3], 0, v[0:1]
	v_lshlrev_b32_e32 v0, 1, v22
	v_or3_b32 v4, v4, v8, v22
	v_lshl_add_u64 v[2:3], v[2:3], 0, v[0:1]
	v_lshlrev_b64 v[6:7], 1, v[4:5]
	v_lshl_add_u64 v[20:21], v[2:3], 0, s[34:35]
	v_add_co_u32_e32 v2, vcc, s2, v2
	v_lshl_add_u64 v[32:33], v[4:5], 2, s[4:5]
	v_lshl_add_u64 v[4:5], s[22:23], 0, v[6:7]
	v_addc_co_u32_e32 v3, vcc, 0, v3, vcc
	global_load_dwordx4 v[8:11], v[4:5], off
	global_load_dwordx4 v[12:15], v[4:5], off offset:16
	v_cmp_lt_i32_e32 vcc, v227, v221
	global_load_dwordx4 v[16:19], v[2:3], off
	s_nop 0
	global_load_dwordx4 v[2:5], v[20:21], off offset:16
	v_cndmask_b32_e32 v20, v220, v227, vcc
	v_cmp_lt_i32_e32 vcc, v226, v221
	v_lshlrev_b32_e32 v70, 2, v20
	v_lshlrev_b32_e32 v0, 2, v22
	v_cndmask_b32_e32 v20, v220, v226, vcc
	v_cmp_lt_i32_e32 vcc, v235, v221
	v_lshlrev_b32_e32 v71, 2, v20
	v_lshl_add_u64 v[6:7], s[28:29], 0, v[6:7]
	v_cndmask_b32_e32 v20, v220, v235, vcc
	v_lshlrev_b32_e32 v72, 2, v20
	global_load_dwordx4 v[20:23], v[32:33], off offset:48
	global_load_dwordx4 v[24:27], v[32:33], off offset:32
	global_load_dwordx4 v[28:31], v[32:33], off offset:16
	s_nop 0
	global_load_dwordx4 v[32:35], v[32:33], off
	s_addk_i32 s20, 0x2000
	s_cmpk_gt_i32 s21, 0x3ff
	s_waitcnt vmcnt(0)
	v_lshlrev_b32_e32 v36, 16, v15
	v_and_b32_e32 v37, 0xffff0000, v15
	s_waitcnt vmcnt(4)
	v_and_b32_e32 v55, 0xffff0000, v4
	v_lshlrev_b32_e32 v58, 16, v3
	v_and_b32_e32 v59, 0xffff0000, v3
	v_lshlrev_b32_e32 v54, 16, v4
	v_mul_f32_e32 v4, 0xbfb8aa3b, v54
	v_exp_f32_e32 v4, v4
	v_lshlrev_b32_e32 v62, 16, v19
	v_and_b32_e32 v63, 0xffff0000, v19
	s_waitcnt vmcnt(3)
	v_pk_add_f32 v[48:49], v[22:23], v[36:37]
	v_lshlrev_b32_e32 v22, 16, v14
	v_and_b32_e32 v23, 0xffff0000, v14
	v_pk_add_f32 v[14:15], v[20:21], v[22:23]
	global_load_dwordx4 v[20:23], v0, s[26:27] offset:48
	global_load_dwordx4 v[36:39], v0, s[26:27] offset:32
	global_load_dwordx4 v[40:43], v0, s[26:27] offset:16
	global_load_dwordx4 v[44:47], v0, s[26:27]
	v_mul_f32_e32 v0, 0xbfb8aa3b, v55
	v_exp_f32_e32 v0, v0
	v_add_f32_e32 v4, 1.0, v4
	v_rcp_f32_e32 v56, v4
	v_lshlrev_b32_e32 v66, 16, v17
	v_add_f32_e32 v0, 1.0, v0
	v_rcp_f32_e32 v57, v0
	v_mul_f32_e32 v0, 0xbfb8aa3b, v58
	v_exp_f32_e32 v0, v0
	v_and_b32_e32 v67, 0xffff0000, v17
	v_pk_mul_f32 v[54:55], v[56:57], v[54:55]
	v_lshlrev_b32_e32 v56, 16, v13
	v_add_f32_e32 v0, 1.0, v0
	v_rcp_f32_e32 v60, v0
	v_mul_f32_e32 v0, 0xbfb8aa3b, v59
	v_exp_f32_e32 v0, v0
	v_and_b32_e32 v57, 0xffff0000, v13
	s_waitcnt vmcnt(6)
	v_pk_add_f32 v[26:27], v[26:27], v[56:57]
	v_pk_mul_f32 v[52:53], v[14:15], v[14:15]
	v_add_f32_e32 v0, 1.0, v0
	v_rcp_f32_e32 v61, v0
	v_pk_mul_f32 v[56:57], v[26:27], v[26:27]
	v_pk_mul_f32 v[50:51], v[48:49], v[48:49]
	v_pk_mul_f32 v[58:59], v[60:61], v[58:59]
	v_lshlrev_b32_e32 v60, 16, v12
	v_and_b32_e32 v61, 0xffff0000, v12
	v_pk_add_f32 v[12:13], v[24:25], v[60:61]
	v_lshlrev_b32_e32 v60, 16, v2
	v_mul_f32_e32 v0, 0xbfb8aa3b, v60
	v_exp_f32_e32 v0, v0
	v_and_b32_e32 v61, 0xffff0000, v2
	v_pk_mul_f32 v[24:25], v[12:13], v[12:13]
	v_add_f32_e32 v0, 1.0, v0
	v_rcp_f32_e32 v2, v0
	v_mul_f32_e32 v0, 0xbfb8aa3b, v61
	v_exp_f32_e32 v0, v0
	s_nop 0
	v_add_f32_e32 v0, 1.0, v0
	v_rcp_f32_e32 v3, v0
	v_mul_f32_e32 v0, 0xbfb8aa3b, v62
	v_exp_f32_e32 v0, v0
	v_pk_mul_f32 v[2:3], v[2:3], v[60:61]
	v_lshlrev_b32_e32 v60, 16, v11
	v_add_f32_e32 v0, 1.0, v0
	v_rcp_f32_e32 v64, v0
	v_mul_f32_e32 v0, 0xbfb8aa3b, v63
	v_exp_f32_e32 v0, v0
	v_and_b32_e32 v61, 0xffff0000, v11
	s_waitcnt vmcnt(5)
	v_pk_add_f32 v[30:31], v[30:31], v[60:61]
	v_add_f32_e32 v0, 1.0, v0
	v_rcp_f32_e32 v65, v0
	v_pk_mul_f32 v[60:61], v[30:31], v[30:31]
	v_pk_mul_f32 v[62:63], v[64:65], v[62:63]
	v_lshlrev_b32_e32 v64, 16, v10
	v_and_b32_e32 v65, 0xffff0000, v10
	v_pk_add_f32 v[10:11], v[28:29], v[64:65]
	v_lshlrev_b32_e32 v64, 16, v18
	v_mul_f32_e32 v0, 0xbfb8aa3b, v64
	v_exp_f32_e32 v0, v0
	v_and_b32_e32 v65, 0xffff0000, v18
	v_pk_mul_f32 v[28:29], v[10:11], v[10:11]
	v_add_f32_e32 v0, 1.0, v0
	v_rcp_f32_e32 v18, v0
	v_mul_f32_e32 v0, 0xbfb8aa3b, v65
	v_exp_f32_e32 v0, v0
	s_nop 0
	v_add_f32_e32 v0, 1.0, v0
	v_rcp_f32_e32 v19, v0
	v_mul_f32_e32 v0, 0xbfb8aa3b, v66
	v_exp_f32_e32 v0, v0
	v_pk_mul_f32 v[18:19], v[18:19], v[64:65]
	v_lshlrev_b32_e32 v64, 16, v9
	v_add_f32_e32 v0, 1.0, v0
	v_rcp_f32_e32 v68, v0
	v_mul_f32_e32 v0, 0xbfb8aa3b, v67
	v_exp_f32_e32 v0, v0
	v_and_b32_e32 v65, 0xffff0000, v9
	s_waitcnt vmcnt(4)
	v_pk_add_f32 v[34:35], v[34:35], v[64:65]
	v_add_f32_e32 v0, 1.0, v0
	v_rcp_f32_e32 v69, v0
	v_pk_mul_f32 v[64:65], v[34:35], v[34:35]
	v_pk_mul_f32 v[66:67], v[68:69], v[66:67]
	v_lshlrev_b32_e32 v68, 16, v8
	v_and_b32_e32 v69, 0xffff0000, v8
	v_pk_add_f32 v[8:9], v[32:33], v[68:69]
	v_lshlrev_b32_e32 v68, 16, v16
	v_mul_f32_e32 v0, 0xbfb8aa3b, v68
	v_exp_f32_e32 v0, v0
	v_and_b32_e32 v69, 0xffff0000, v16
	v_pk_mul_f32 v[32:33], v[8:9], v[8:9]
	v_add_f32_e32 v0, 1.0, v0
	v_rcp_f32_e32 v16, v0
	v_mul_f32_e32 v0, 0xbfb8aa3b, v69
	v_exp_f32_e32 v0, v0
	s_nop 0
	v_add_f32_e32 v0, 1.0, v0
	v_rcp_f32_e32 v17, v0
	v_add_f32_e32 v0, v32, v33
	v_add_f32_e32 v0, v64, v0
	v_add_f32_e32 v0, v65, v0
	v_add_f32_e32 v0, v28, v0
	v_add_f32_e32 v0, v29, v0
	v_add_f32_e32 v0, v60, v0
	v_add_f32_e32 v0, v61, v0
	v_add_f32_e32 v0, v24, v0
	v_add_f32_e32 v0, v25, v0
	v_add_f32_e32 v0, v56, v0
	v_add_f32_e32 v0, v57, v0
	v_add_f32_e32 v0, v52, v0
	v_add_f32_e32 v0, v53, v0
	v_add_f32_e32 v0, v50, v0
	v_add_f32_e32 v0, v51, v0
	ds_bpermute_b32 v4, v70, v0
	v_pk_mul_f32 v[16:17], v[16:17], v[68:69]
	s_waitcnt lgkmcnt(0)
	v_add_f32_e32 v0, v0, v4
	ds_bpermute_b32 v4, v71, v0
	s_waitcnt lgkmcnt(0)
	v_add_f32_e32 v0, v0, v4
	ds_bpermute_b32 v4, v72, v0
	s_waitcnt lgkmcnt(0)
	v_add_f32_e32 v0, v0, v4
	v_fmamk_f32 v0, v0, 0x3c000000, v187
	v_cmp_gt_f32_e32 vcc, s82, v0
	v_mul_f32_e32 v4, 0x4b800000, v0
	s_nop 0
	v_cndmask_b32_e32 v0, v0, v4, vcc
	v_rsq_f32_e32 v0, v0
	s_nop 0
	v_mul_f32_e32 v4, 0x45800000, v0
	v_cndmask_b32_e32 v0, v0, v4, vcc
	v_pk_mul_f32 v[12:13], v[12:13], v[0:1] op_sel_hi:[1,0]
	v_pk_mul_f32 v[8:9], v[8:9], v[0:1] op_sel_hi:[1,0]
	s_waitcnt vmcnt(2)
	v_pk_mul_f32 v[12:13], v[36:37], v[12:13]
	s_waitcnt vmcnt(0)
	v_pk_mul_f32 v[8:9], v[44:45], v[8:9]
	v_pk_mul_f32 v[12:13], v[2:3], v[12:13]
	v_pk_mul_f32 v[2:3], v[34:35], v[0:1] op_sel_hi:[1,0]
	v_pk_mul_f32 v[8:9], v[16:17], v[8:9]
	v_pk_mul_f32 v[2:3], v[46:47], v[2:3]
	s_nop 0
	v_pk_mul_f32 v[16:17], v[66:67], v[2:3]
	v_pk_mul_f32 v[2:3], v[26:27], v[0:1] op_sel_hi:[1,0]
	s_nop 0
	v_pk_mul_f32 v[2:3], v[38:39], v[2:3]
	s_nop 0
	v_pk_mul_f32 v[24:25], v[58:59], v[2:3]
	v_pk_mul_f32 v[2:3], v[10:11], v[0:1] op_sel_hi:[1,0]
	s_nop 0
	v_pk_mul_f32 v[2:3], v[40:41], v[2:3]
	s_nop 0
	v_pk_mul_f32 v[10:11], v[18:19], v[2:3]
	v_pk_mul_f32 v[2:3], v[14:15], v[0:1] op_sel_hi:[1,0]
	s_nop 0
	v_pk_mul_f32 v[2:3], v[20:21], v[2:3]
	v_pk_mul_f32 v[20:21], v[48:49], v[0:1] op_sel_hi:[1,0]
	v_pk_mul_f32 v[14:15], v[54:55], v[2:3]
	v_pk_mul_f32 v[2:3], v[30:31], v[0:1] op_sel_hi:[1,0]
	v_pk_mul_f32 v[20:21], v[22:23], v[20:21]
	v_pk_mul_f32 v[2:3], v[42:43], v[2:3]
	s_nop 0
	v_pk_mul_f32 v[18:19], v[62:63], v[2:3]
	v_lshlrev_b32_e32 v2, 16, v5
	v_and_b32_e32 v3, 0xffff0000, v5
	v_mul_f32_e32 v4, 0xbfb8aa3b, v2
	v_mul_f32_e32 v0, 0xbfb8aa3b, v3
	v_exp_f32_e32 v4, v4
	v_exp_f32_e32 v0, v0
	v_add_f32_e32 v4, 1.0, v4
	v_add_f32_e32 v0, 1.0, v0
	v_rcp_f32_e32 v4, v4
	v_rcp_f32_e32 v5, v0
	s_nop 0
	v_pk_mul_f32 v[2:3], v[4:5], v[2:3]
	s_nop 0
	v_pk_mul_f32 v[20:21], v[2:3], v[20:21]
	v_cvt_pk_bf16_f32 v2, v8, v9
	v_cvt_pk_bf16_f32 v3, v16, v17
	v_cvt_pk_bf16_f32 v4, v10, v11
	v_cvt_pk_bf16_f32 v5, v18, v19
	global_store_dwordx4 v[6:7], v[2:5], off
	s_nop 1
	v_cvt_pk_bf16_f32 v2, v12, v13
	v_cvt_pk_bf16_f32 v3, v24, v25
	v_cvt_pk_bf16_f32 v4, v14, v15
	v_cvt_pk_bf16_f32 v5, v20, v21
	global_store_dwordx4 v[6:7], v[2:5], off offset:16
	s_cbranch_scc0 .LBB0_223

.Lp2done:
	s_waitcnt vmcnt(0) lgkmcnt(0)
	s_barrier
	s_cmp_lg_u32 s80, 0
	s_cbranch_scc1 .Lp2done_x
	buffer_wbl2 sc1
	s_waitcnt vmcnt(0)
	v_readlane_b32 s98, v255, 13
	v_readlane_b32 s99, v255, 14
	s_mov_b64 s[4:5], exec
	s_mov_b64 exec, 1
	v_mov_b32_e32 v2, 1
	s_nop 4
	global_atomic_add v1, v2, s[98:99]
	s_mov_b64 exec, s[4:5]
.Lp2done_x:
.LBB0_227:
	s_mov_b64 s[4:5], -1
